# E41: E40 + attention run-end output ladder de-serialised (second gate and all eight aof fragments loaded up front, one wait)
# speedup vs baseline: 1.0026x; 1.0004x over previous
.LBB0_4463:
	ds_bpermute_b32 v3, v220, v194
	s_add_i32 s72, s89, s88
	s_waitcnt lgkmcnt(0)
	v_add_f32_e32 v3, v194, v3
	ds_bpermute_b32 v4, v221, v3
	s_waitcnt lgkmcnt(0)
	v_add_f32_e32 v3, v3, v4
	v_lshl_add_u64 v[4:5], s[72:73], 2, v[106:107]
	global_load_dword v54, v[4:5], off
	global_load_dword v238, v[4:5], off offset:12
	global_load_dwordx4 v[62:65], v[154:155], off
	global_load_dwordx4 v[66:69], v[158:159], off
	global_load_dwordx4 v[70:73], v[162:163], off
	global_load_dwordx4 v[74:77], v[166:167], off
	global_load_dwordx4 v[78:81], v[170:171], off
	global_load_dwordx4 v[82:85], v[174:175], off
	global_load_dwordx4 v[86:89], v[182:183], off
	global_load_dwordx4 v[90:93], v[186:187], off
	v_max_f32_e32 v3, 0xda24260, v3
	s_waitcnt vmcnt(0)
	v_div_scale_f32 v55, s[0:1], v3, v3, v54
	v_rcp_f32_e32 v56, v55
	s_mov_b64 s[0:1], -1
	v_fma_f32 v57, -v55, v56, 1.0
	v_fmac_f32_e32 v56, v57, v56
	v_div_scale_f32 v57, vcc, v54, v3, v54
	v_mul_f32_e32 v58, v57, v56
	v_fma_f32 v59, -v55, v58, v57
	v_fmac_f32_e32 v58, v59, v56
	v_fma_f32 v55, -v55, v58, v57
	v_div_fmas_f32 v55, v55, v56, v58
	s_nop 1
	v_mov_b64_e32 v[56:57], v[62:63]
	v_mov_b64_e32 v[58:59], v[64:65]
	v_div_fixup_f32 v54, v55, v3, v54
	s_and_b64 vcc, exec, s[80:81]
	v_pk_fma_f32 v[52:53], v[52:53], v[54:55], v[58:59] op_sel_hi:[1,0,1]
	v_pk_fma_f32 v[50:51], v[50:51], v[54:55], v[56:57] op_sel_hi:[1,0,1]
	s_cbranch_vccz .LBB0_4465
	v_cvt_pk_bf16_f32 v56, v50, v51
	v_cvt_pk_bf16_f32 v57, v52, v53
	global_store_dwordx2 v[156:157], v[56:57], off
	s_mov_b64 s[0:1], 0

.LBB0_4467:
	s_nop 1
	v_mov_b64_e32 v[50:51], v[66:67]
	v_mov_b64_e32 v[52:53], v[68:69]
	v_mov_b32_e32 v55, v54
	v_mov_b32_e32 v56, v54
	v_mov_b32_e32 v57, v54
	v_cndmask_b32_e64 v3, 0, 1, s[80:81]
	v_cmp_ne_u32_e64 s[0:1], 1, v3
	s_andn2_b64 vcc, exec, s[80:81]
	s_mov_b64 s[2:3], -1
	v_pk_fma_f32 v[48:49], v[48:49], v[56:57], v[52:53]
	v_pk_fma_f32 v[46:47], v[46:47], v[54:55], v[50:51]
	s_cbranch_vccnz .LBB0_4469
	s_mov_b64 s[2:3], 0
	v_cvt_pk_bf16_f32 v50, v46, v47
	v_cvt_pk_bf16_f32 v51, v48, v49
	global_store_dwordx2 v[160:161], v[50:51], off

.LBB0_4471:
	s_nop 1
	v_mov_b64_e32 v[46:47], v[70:71]
	v_mov_b64_e32 v[48:49], v[72:73]
	v_mov_b32_e32 v50, v54
	v_mov_b32_e32 v51, v54
	s_and_b64 vcc, exec, s[0:1]
	s_mov_b64 s[2:3], -1
	v_pk_fma_f32 v[44:45], v[44:45], v[50:51], v[48:49]
	v_pk_fma_f32 v[42:43], v[42:43], v[54:55], v[46:47]
	s_cbranch_vccnz .LBB0_4473
	s_mov_b64 s[2:3], 0
	v_cvt_pk_bf16_f32 v46, v42, v43
	v_cvt_pk_bf16_f32 v47, v44, v45
	global_store_dwordx2 v[164:165], v[46:47], off

.LBB0_4475:
	s_nop 1
	v_mov_b64_e32 v[42:43], v[74:75]
	v_mov_b64_e32 v[44:45], v[76:77]
	v_mov_b32_e32 v46, v54
	v_mov_b32_e32 v47, v54
	s_and_b64 vcc, exec, s[0:1]
	s_mov_b64 s[2:3], -1
	v_pk_fma_f32 v[40:41], v[40:41], v[46:47], v[44:45]
	v_pk_fma_f32 v[38:39], v[38:39], v[54:55], v[42:43]
	s_cbranch_vccnz .LBB0_4477
	s_mov_b64 s[2:3], 0
	v_cvt_pk_bf16_f32 v42, v38, v39
	v_cvt_pk_bf16_f32 v43, v40, v41
	global_store_dwordx2 v[168:169], v[42:43], off

.LBB0_4479:
	v_mov_b32_e32 v4, v238
	ds_bpermute_b32 v3, v220, v195
	s_waitcnt lgkmcnt(0)
	v_add_f32_e32 v3, v195, v3
	ds_bpermute_b32 v38, v221, v3
	s_waitcnt lgkmcnt(0)
	v_add_f32_e32 v3, v3, v38
	v_max_f32_e32 v3, 0xda24260, v3
	v_div_scale_f32 v5, s[2:3], v3, v3, v4
	v_rcp_f32_e32 v38, v5
	s_mov_b64 s[2:3], -1
	v_fma_f32 v39, -v5, v38, 1.0
	v_fmac_f32_e32 v38, v39, v38
	v_div_scale_f32 v39, vcc, v4, v3, v4
	v_mul_f32_e32 v40, v39, v38
	v_fma_f32 v41, -v5, v40, v39
	v_fmac_f32_e32 v40, v41, v38
	v_fma_f32 v5, -v5, v40, v39
	v_div_fmas_f32 v5, v5, v38, v40
	s_nop 1
	v_mov_b64_e32 v[38:39], v[78:79]
	v_mov_b64_e32 v[40:41], v[80:81]
	v_div_fixup_f32 v4, v5, v3, v4
	s_and_b64 vcc, exec, s[0:1]
	v_pk_fma_f32 v[36:37], v[36:37], v[4:5], v[40:41] op_sel_hi:[1,0,1]
	v_pk_fma_f32 v[34:35], v[34:35], v[4:5], v[38:39] op_sel_hi:[1,0,1]
	s_cbranch_vccnz .LBB0_4481
	s_mov_b64 s[2:3], 0
	v_cvt_pk_bf16_f32 v38, v34, v35
	v_cvt_pk_bf16_f32 v39, v36, v37
	global_store_dwordx2 v[172:173], v[38:39], off

.LBB0_4483:
	s_nop 1
	v_mov_b64_e32 v[34:35], v[82:83]
	v_mov_b64_e32 v[36:37], v[84:85]
	v_mov_b32_e32 v5, v4
	v_mov_b32_e32 v38, v4
	v_mov_b32_e32 v39, v4
	s_and_b64 vcc, exec, s[0:1]
	s_mov_b64 s[2:3], -1
	v_pk_fma_f32 v[32:33], v[32:33], v[38:39], v[36:37]
	v_pk_fma_f32 v[30:31], v[30:31], v[4:5], v[34:35]
	s_cbranch_vccnz .LBB0_4485
	s_mov_b64 s[2:3], 0
	v_cvt_pk_bf16_f32 v34, v30, v31
	v_cvt_pk_bf16_f32 v35, v32, v33
	global_store_dwordx2 v[176:177], v[34:35], off

.LBB0_4487:
	s_nop 1
	v_mov_b64_e32 v[30:31], v[86:87]
	v_mov_b64_e32 v[32:33], v[88:89]
	v_mov_b32_e32 v34, v4
	v_mov_b32_e32 v35, v4
	s_and_b64 vcc, exec, s[0:1]
	s_mov_b64 s[2:3], -1
	v_pk_fma_f32 v[28:29], v[28:29], v[34:35], v[32:33]
	v_pk_fma_f32 v[26:27], v[26:27], v[4:5], v[30:31]
	s_cbranch_vccnz .LBB0_4489
	s_mov_b64 s[2:3], 0
	v_cvt_pk_bf16_f32 v30, v26, v27
	v_cvt_pk_bf16_f32 v31, v28, v29
	global_store_dwordx2 v[184:185], v[30:31], off

.LBB0_4491:
	s_nop 1
	v_mov_b64_e32 v[26:27], v[90:91]
	v_mov_b64_e32 v[28:29], v[92:93]
	v_mov_b32_e32 v30, v4
	v_mov_b32_e32 v31, v4
	s_and_b64 vcc, exec, s[0:1]
	s_mov_b64 s[0:1], -1
	v_pk_fma_f32 v[24:25], v[24:25], v[30:31], v[28:29]
	v_pk_fma_f32 v[22:23], v[22:23], v[4:5], v[26:27]
	s_cbranch_vccnz .LBB0_4493
	s_mov_b64 s[0:1], 0
	v_cvt_pk_bf16_f32 v4, v22, v23
	v_cvt_pk_bf16_f32 v5, v24, v25
	global_store_dwordx2 v[188:189], v[4:5], off
